# v29 + P2: rotary cos/sin table entries loaded once per token (stashed in free VGPRs) instead of at each of 7 use sites; 5 load+vmcnt(0) round trips removed per sample token
# speedup vs baseline: 1.0124x; 1.0007x over previous
.LBB0_646:
	v_lshl_add_u64 v[66:67], s[24:25], 0, v[124:125]
	global_load_dwordx2 v[154:155], v[66:67], off
	global_load_dwordx4 v[70:73], v[76:77], off
	global_load_dwordx2 v[68:69], v[66:67], off offset:512
	global_load_dwordx2 v[156:157], v[66:67], off offset:2560
	global_load_dwordx2 v[152:153], v[66:67], off offset:3072
	s_movk_i32 s0, 0x1000
	v_add_co_u32_e32 v142, vcc, s0, v66
	v_add_u32_e32 v173, 8, v173
	s_nop 0
	v_addc_co_u32_e32 v143, vcc, 0, v67, vcc
	global_load_dwordx2 v[150:151], v[66:67], off offset:3584
	global_load_dwordx2 v[146:147], v[142:143], off
	s_waitcnt lgkmcnt(0)
	global_load_dwordx2 v[148:149], v[142:143], off offset:512
	global_load_dwordx2 v[144:145], v[142:143], off offset:1024
	s_nop 0
	global_load_dwordx2 v[142:143], v[142:143], off offset:1536
	v_add_u32_e32 v180, s59, v173
	s_andn2_b64 vcc, exec, s[12:13]
	s_waitcnt vmcnt(0)
	v_lshlrev_b32_e32 v66, 16, v154
	v_and_b32_e32 v67, 0xffff0000, v154
	v_lshlrev_b32_e32 v154, 16, v155
	v_and_b32_e32 v155, 0xffff0000, v155
	v_pk_mul_f32 v[176:177], v[66:67], v[66:67]
	v_pk_mul_f32 v[178:179], v[154:155], v[154:155]
	v_add_f32_e32 v176, v176, v177
	v_add_f32_e32 v176, v178, v176
	v_add_f32_e32 v176, v179, v176
	s_nop 1
	v_mov_b32_dpp v177, v176 quad_perm:[1,0,3,2] row_mask:0xf bank_mask:0xf
	v_cndmask_b32_e64 v179, 0, 1, s[12:13]
	v_cmp_ne_u32_e64 s[72:73], 1, v179
	s_waitcnt lgkmcnt(0)
	v_add_f32_e32 v176, v176, v177
	s_nop 1
	v_mov_b32_dpp v177, v176 quad_perm:[2,3,0,1] row_mask:0xf bank_mask:0xf
	s_waitcnt lgkmcnt(0)
	v_add_f32_e32 v176, v176, v177
	s_nop 1
	v_mov_b32_dpp v177, v176 row_shl:4 row_mask:0xf bank_mask:0x5
	v_mov_b32_dpp v177, v176 row_shr:4 row_mask:0xf bank_mask:0xa
	s_waitcnt lgkmcnt(0)
	v_add_f32_e32 v177, v176, v177
	s_nop 1
	v_mov_b32_dpp v178, v177 row_ror:8 row_mask:0xf bank_mask:0xf
	v_and_b32_e32 v176, 63, v173
	s_waitcnt lgkmcnt(0)
	v_add_f32_e32 v177, v177, v178
	v_fmamk_f32 v177, v177, 0x3c800000, v219
	v_mul_f32_e32 v178, 0x4b800000, v177
	v_cmp_gt_f32_e64 s[0:1], s33, v177
	s_nop 1
	v_cndmask_b32_e64 v177, v177, v178, s[0:1]
	v_rsq_f32_e32 v178, v177
	v_ashrrev_i32_e32 v177, 6, v180
	v_mul_f32_e32 v179, 0x45800000, v178
	v_cndmask_b32_e64 v178, v178, v179, s[0:1]
	v_pk_mul_f32 v[70:71], v[70:71], v[178:179] op_sel_hi:[1,0]
	v_pk_mul_f32 v[72:73], v[72:73], v[178:179] op_sel_hi:[1,0]
	v_pk_mul_f32 v[70:71], v[70:71], v[66:67]
	v_pk_mul_f32 v[66:67], v[72:73], v[154:155]
	v_cndmask_b32_e64 v178, v176, v177, s[40:41]
	s_cbranch_vccnz .LBB0_648
	v_lshl_or_b32 v154, v178, 5, v159
	v_readlane_b32 s0, v250, 10
	v_ashrrev_i32_e32 v155, 31, v154
	v_readlane_b32 s1, v250, 11
	v_mov_b32_dpp v72, v70 row_shl:4 row_mask:0xf bank_mask:0x5
	v_mov_b32_dpp v72, v70 row_shr:4 row_mask:0xf bank_mask:0xa
	v_mov_b32_dpp v73, v71 row_shl:4 row_mask:0xf bank_mask:0x5
	v_mov_b32_dpp v73, v71 row_shr:4 row_mask:0xf bank_mask:0xa
	v_lshl_add_u64 v[154:155], v[154:155], 2, s[0:1]
	global_load_dwordx4 v[180:183], v[154:155], off offset:16
	global_load_dwordx4 v[184:187], v[154:155], off
	s_waitcnt vmcnt(0)
	v_mov_b32_e32 v190, v184
	v_mov_b32_e32 v194, v180
	v_mov_b32_e32 v191, v185
	v_mov_b32_e32 v195, v181
	v_mov_b32_e32 v192, v186
	v_mov_b32_e32 v196, v182
	v_mov_b32_e32 v193, v187
	v_mov_b32_e32 v197, v183
	v_mov_b32_e32 v155, v186
	v_mov_b32_e32 v186, v185
	s_waitcnt lgkmcnt(0)
	v_pk_mul_f32 v[72:73], v[186:187], v[72:73]
	v_mov_b32_e32 v154, v184
	v_cndmask_b32_e64 v73, v73, -v73, s[42:43]
	v_cndmask_b32_e64 v72, v72, -v72, s[42:43]
	v_pk_fma_f32 v[70:71], v[70:71], v[154:155], v[72:73]
	v_mov_b32_dpp v72, v66 row_shl:4 row_mask:0xf bank_mask:0x5
	v_mov_b32_dpp v72, v66 row_shr:4 row_mask:0xf bank_mask:0xa
	v_mov_b32_dpp v73, v67 row_shl:4 row_mask:0xf bank_mask:0x5
	v_mov_b32_dpp v73, v67 row_shr:4 row_mask:0xf bank_mask:0xa
	v_mov_b32_e32 v155, v182
	v_mov_b32_e32 v182, v181
	v_mov_b32_e32 v154, v180
	s_waitcnt lgkmcnt(0)
	v_pk_mul_f32 v[72:73], v[182:183], v[72:73]
	s_nop 0
	v_cndmask_b32_e64 v73, v73, -v73, s[42:43]
	v_cndmask_b32_e64 v72, v72, -v72, s[42:43]
	v_pk_fma_f32 v[66:67], v[66:67], v[154:155], v[72:73]
.LBB0_648:
	s_mov_b32 s0, 0x3e38aa3b
	v_pk_mul_f32 v[70:71], v[70:71], s[0:1] op_sel_hi:[1,0]
	v_pk_mul_f32 v[66:67], v[66:67], s[0:1] op_sel_hi:[1,0]
	v_lshl_add_u64 v[154:155], s[24:25], 0, v[130:131]
	v_cvt_pk_bf16_f32 v70, v70, v71
	v_cvt_pk_bf16_f32 v71, v66, v67
	v_add_co_u32_e32 v66, vcc, 0x13000000, v154
	s_nop 1
	v_addc_co_u32_e32 v67, vcc, 0, v155, vcc
	global_store_dwordx2 v[66:67], v[70:71], off
	global_load_dwordx4 v[70:73], v[78:79], off
	v_lshlrev_b32_e32 v66, 16, v68
	v_and_b32_e32 v67, 0xffff0000, v68
	v_pk_mul_f32 v[180:181], v[66:67], v[66:67]
	v_lshlrev_b32_e32 v68, 16, v69
	v_and_b32_e32 v69, 0xffff0000, v69
	v_pk_mul_f32 v[182:183], v[68:69], v[68:69]
	v_add_f32_e32 v179, v180, v181
	v_add_f32_e32 v179, v182, v179
	v_add_f32_e32 v179, v183, v179
	s_nop 1
	v_mov_b32_dpp v180, v179 quad_perm:[1,0,3,2] row_mask:0xf bank_mask:0xf
	s_waitcnt lgkmcnt(0)
	v_add_f32_e32 v179, v179, v180
	s_nop 1
	v_mov_b32_dpp v180, v179 quad_perm:[2,3,0,1] row_mask:0xf bank_mask:0xf
	s_waitcnt lgkmcnt(0)
	v_add_f32_e32 v179, v179, v180
	s_nop 1
	v_mov_b32_dpp v180, v179 row_shl:4 row_mask:0xf bank_mask:0x5
	v_mov_b32_dpp v180, v179 row_shr:4 row_mask:0xf bank_mask:0xa
	s_waitcnt lgkmcnt(0)
	v_add_f32_e32 v179, v179, v180
	s_nop 1
	v_mov_b32_dpp v180, v179 row_ror:8 row_mask:0xf bank_mask:0xf
	s_waitcnt lgkmcnt(0)
	v_add_f32_e32 v179, v179, v180
	v_fmamk_f32 v179, v179, 0x3c800000, v219
	v_cmp_gt_f32_e32 vcc, s33, v179
	v_mul_f32_e32 v180, 0x4b800000, v179
	s_nop 0
	v_cndmask_b32_e32 v179, v179, v180, vcc
	v_rsq_f32_e32 v179, v179
	s_nop 0
	v_mul_f32_e32 v180, 0x45800000, v179
	v_cndmask_b32_e32 v180, v179, v180, vcc
	v_pk_mul_f32 v[182:183], v[180:181], v[66:67] op_sel_hi:[0,1]
	v_pk_mul_f32 v[180:181], v[180:181], v[68:69] op_sel_hi:[0,1]
	s_and_b64 vcc, exec, s[72:73]
	s_waitcnt vmcnt(0)
	v_pk_mul_f32 v[70:71], v[70:71], v[182:183]
	v_pk_mul_f32 v[72:73], v[72:73], v[180:181]
	s_cbranch_vccnz .LBB0_650
	v_lshl_or_b32 v178, v178, 5, v159
	v_readlane_b32 s0, v250, 10
	v_ashrrev_i32_e32 v179, 31, v178
	v_readlane_b32 s1, v250, 11
	v_mov_b32_dpp v186, v70 row_shl:4 row_mask:0xf bank_mask:0x5
	v_mov_b32_dpp v186, v70 row_shr:4 row_mask:0xf bank_mask:0xa
	v_mov_b32_dpp v187, v71 row_shl:4 row_mask:0xf bank_mask:0x5
	v_mov_b32_dpp v187, v71 row_shr:4 row_mask:0xf bank_mask:0xa
	v_lshl_add_u64 v[182:183], v[178:179], 2, s[0:1]
	s_nop 1
	v_mov_b32_e32 v182, v190
	v_mov_b32_e32 v178, v194
	v_mov_b32_e32 v183, v191
	v_mov_b32_e32 v179, v195
	v_mov_b32_e32 v184, v192
	v_mov_b32_e32 v180, v196
	v_mov_b32_e32 v185, v193
	v_mov_b32_e32 v181, v197
	v_mov_b32_e32 v189, v184
	v_mov_b32_e32 v184, v183
	v_mov_b32_e32 v188, v182
	s_waitcnt lgkmcnt(0)
	v_pk_mul_f32 v[182:183], v[184:185], v[186:187]
	v_mov_b32_e32 v185, v180
	v_cndmask_b32_e64 v183, v183, -v183, s[42:43]
	v_cndmask_b32_e64 v182, v182, -v182, s[42:43]
	v_pk_fma_f32 v[70:71], v[70:71], v[188:189], v[182:183]
	v_mov_b32_dpp v182, v72 row_shl:4 row_mask:0xf bank_mask:0x5
	v_mov_b32_dpp v182, v72 row_shr:4 row_mask:0xf bank_mask:0xa
	v_mov_b32_dpp v183, v73 row_shl:4 row_mask:0xf bank_mask:0x5
	v_mov_b32_dpp v183, v73 row_shr:4 row_mask:0xf bank_mask:0xa
	v_mov_b32_e32 v180, v179
	v_mov_b32_e32 v184, v178
	s_waitcnt lgkmcnt(0)
	v_pk_mul_f32 v[178:179], v[180:181], v[182:183]
	s_nop 0
	v_cndmask_b32_e64 v179, v179, -v179, s[42:43]
	v_cndmask_b32_e64 v178, v178, -v178, s[42:43]
	v_pk_fma_f32 v[72:73], v[72:73], v[184:185], v[178:179]

.LBB0_656:
	s_or_b64 exec, exec, s[8:9]
	v_lshlrev_b32_e32 v66, 16, v156
	v_and_b32_e32 v67, 0xffff0000, v156
	v_lshlrev_b32_e32 v68, 16, v157
	v_and_b32_e32 v69, 0xffff0000, v157
	s_and_b64 vcc, exec, s[72:73]
	v_cndmask_b32_e64 v156, v176, v177, s[42:43]
	s_cbranch_vccnz .LBB0_658
	v_lshl_or_b32 v70, v156, 4, v160
	v_readlane_b32 s8, v251, 13
	v_ashrrev_i32_e32 v71, 31, v70
	v_readlane_b32 s9, v251, 14
	v_mov_b32_dpp v180, v66 quad_perm:[2,3,0,1] row_mask:0xf bank_mask:0xf
	v_mov_b32_dpp v181, v67 quad_perm:[2,3,0,1] row_mask:0xf bank_mask:0xf
	v_lshl_add_u64 v[176:177], v[70:71], 2, s[8:9]
	global_load_dwordx4 v[70:73], v[176:177], off offset:16
	s_nop 0
	global_load_dwordx4 v[176:179], v[176:177], off
	s_waitcnt vmcnt(0)
	v_mov_b32_e32 v198, v176
	v_mov_b32_e32 v202, v70
	v_mov_b32_e32 v199, v177
	v_mov_b32_e32 v203, v71
	v_mov_b32_e32 v200, v178
	v_mov_b32_e32 v204, v72
	v_mov_b32_e32 v201, v179
	v_mov_b32_e32 v205, v73
	v_mov_b32_e32 v183, v178
	v_mov_b32_e32 v178, v177
	v_mov_b32_e32 v182, v176
	s_waitcnt lgkmcnt(0)
	v_pk_mul_f32 v[176:177], v[178:179], v[180:181]
	v_mov_b32_e32 v179, v72
	v_cndmask_b32_e64 v177, v177, -v177, s[46:47]
	v_cndmask_b32_e64 v176, v176, -v176, s[46:47]
	v_pk_fma_f32 v[66:67], v[182:183], v[66:67], v[176:177]
	v_mov_b32_dpp v176, v68 quad_perm:[2,3,0,1] row_mask:0xf bank_mask:0xf
	v_mov_b32_dpp v177, v69 quad_perm:[2,3,0,1] row_mask:0xf bank_mask:0xf
	v_mov_b32_e32 v72, v71
	v_mov_b32_e32 v178, v70
	s_waitcnt lgkmcnt(0)
	v_pk_mul_f32 v[70:71], v[72:73], v[176:177]
	s_nop 0
	v_cndmask_b32_e64 v71, v71, -v71, s[46:47]
	v_cndmask_b32_e64 v70, v70, -v70, s[46:47]
	v_pk_fma_f32 v[68:69], v[178:179], v[68:69], v[70:71]
.LBB0_658:
	s_mov_b32 s8, 0x3e8293ee
	v_pk_mul_f32 v[66:67], v[66:67], s[8:9] op_sel_hi:[1,0]
	v_pk_mul_f32 v[68:69], v[68:69], s[8:9] op_sel_hi:[1,0]
	s_brev_b32 s8, 40
	v_cvt_pk_bf16_f32 v66, v66, v67
	v_cvt_pk_bf16_f32 v67, v68, v69
	v_add_co_u32_e32 v68, vcc, s8, v154
	s_nop 1
	v_addc_co_u32_e32 v69, vcc, 0, v155, vcc
	global_store_dwordx2 v[68:69], v[66:67], off
	v_lshlrev_b32_e32 v66, 16, v152
	v_and_b32_e32 v67, 0xffff0000, v152
	v_lshlrev_b32_e32 v68, 16, v153
	s_and_b64 vcc, exec, s[72:73]
	v_and_b32_e32 v69, 0xffff0000, v153
	s_cbranch_vccnz .LBB0_660
	v_lshl_or_b32 v70, v156, 4, v160
	v_readlane_b32 s8, v251, 13
	v_ashrrev_i32_e32 v71, 31, v70
	v_readlane_b32 s9, v251, 14
	v_mov_b32_dpp v152, v66 quad_perm:[2,3,0,1] row_mask:0xf bank_mask:0xf
	v_mov_b32_dpp v153, v67 quad_perm:[2,3,0,1] row_mask:0xf bank_mask:0xf
	v_lshl_add_u64 v[176:177], v[70:71], 2, s[8:9]
	s_nop 1
	v_mov_b32_e32 v176, v198
	v_mov_b32_e32 v70, v202
	v_mov_b32_e32 v177, v199
	v_mov_b32_e32 v71, v203
	v_mov_b32_e32 v178, v200
	v_mov_b32_e32 v72, v204
	v_mov_b32_e32 v179, v201
	v_mov_b32_e32 v73, v205
	v_mov_b32_e32 v181, v178
	v_mov_b32_e32 v178, v177
	s_waitcnt lgkmcnt(0)
	v_pk_mul_f32 v[152:153], v[178:179], v[152:153]
	v_mov_b32_e32 v180, v176
	v_cndmask_b32_e64 v153, v153, -v153, s[46:47]
	v_cndmask_b32_e64 v152, v152, -v152, s[46:47]
	v_pk_fma_f32 v[66:67], v[180:181], v[66:67], v[152:153]
	v_mov_b32_dpp v152, v68 quad_perm:[2,3,0,1] row_mask:0xf bank_mask:0xf
	v_mov_b32_dpp v153, v69 quad_perm:[2,3,0,1] row_mask:0xf bank_mask:0xf
	v_mov_b32_e32 v177, v72
	v_mov_b32_e32 v72, v71
	v_mov_b32_e32 v176, v70
	s_waitcnt lgkmcnt(0)
	v_pk_mul_f32 v[70:71], v[72:73], v[152:153]
	s_nop 0
	v_cndmask_b32_e64 v71, v71, -v71, s[46:47]
	v_cndmask_b32_e64 v70, v70, -v70, s[46:47]
	v_pk_fma_f32 v[68:69], v[176:177], v[68:69], v[70:71]

.LBB0_670:
	v_lshl_or_b32 v70, v156, 4, v160
	v_readlane_b32 s8, v251, 13
	v_ashrrev_i32_e32 v71, 31, v70
	v_readlane_b32 s9, v251, 14
	v_mov_b32_dpp v152, v66 quad_perm:[2,3,0,1] row_mask:0xf bank_mask:0xf
	v_mov_b32_dpp v153, v67 quad_perm:[2,3,0,1] row_mask:0xf bank_mask:0xf
	s_waitcnt lgkmcnt(0)
	v_lshl_add_u64 v[148:149], v[70:71], 2, s[8:9]
	s_nop 1
	v_mov_b32_e32 v148, v198
	v_mov_b32_e32 v70, v202
	v_mov_b32_e32 v149, v199
	v_mov_b32_e32 v71, v203
	v_mov_b32_e32 v150, v200
	v_mov_b32_e32 v72, v204
	v_mov_b32_e32 v151, v201
	v_mov_b32_e32 v73, v205
	v_mov_b32_e32 v155, v150
	v_mov_b32_e32 v150, v149
	v_mov_b32_e32 v154, v148
	s_waitcnt lgkmcnt(0)
	v_pk_mul_f32 v[148:149], v[150:151], v[152:153]
	v_mov_b32_e32 v151, v72
	v_cndmask_b32_e64 v149, v149, -v149, s[46:47]
	v_cndmask_b32_e64 v148, v148, -v148, s[46:47]
	v_pk_fma_f32 v[66:67], v[154:155], v[66:67], v[148:149]
	v_mov_b32_dpp v148, v68 quad_perm:[2,3,0,1] row_mask:0xf bank_mask:0xf
	v_mov_b32_dpp v149, v69 quad_perm:[2,3,0,1] row_mask:0xf bank_mask:0xf
	v_mov_b32_e32 v72, v71
	v_mov_b32_e32 v150, v70
	s_waitcnt lgkmcnt(0)
	v_pk_mul_f32 v[70:71], v[72:73], v[148:149]
	s_nop 0
	v_cndmask_b32_e64 v71, v71, -v71, s[46:47]
	v_cndmask_b32_e64 v70, v70, -v70, s[46:47]
	v_pk_fma_f32 v[68:69], v[150:151], v[68:69], v[70:71]
	s_and_saveexec_b64 s[8:9], s[56:57]
	s_cbranch_execz .LBB0_674

.LBB0_674:
	s_or_b64 exec, exec, s[8:9]
	s_waitcnt lgkmcnt(0)
	v_add_f32_e32 v66, v146, v147
	v_fmamk_f32 v66, v66, 0x3baaaaab, v219
	v_mul_f32_e32 v67, 0x4b800000, v66
	v_cmp_gt_f32_e32 vcc, s33, v66
	s_nop 1
	v_cndmask_b32_e32 v66, v66, v67, vcc
	v_rsq_f32_e32 v68, v66
	v_lshlrev_b32_e32 v66, 16, v144
	v_and_b32_e32 v67, 0xffff0000, v144
	v_mul_f32_e32 v69, 0x45800000, v68
	v_cndmask_b32_e32 v68, v68, v69, vcc
	v_pk_mul_f32 v[70:71], v[68:69], v[66:67] op_sel_hi:[0,1]
	v_lshlrev_b32_e32 v66, 16, v145
	v_and_b32_e32 v67, 0xffff0000, v145
	v_pk_mul_f32 v[72:73], v[68:69], v[66:67] op_sel_hi:[0,1]
	s_and_b64 vcc, exec, s[72:73]
	v_mov_b32_e32 v144, v70
	v_mov_b32_e32 v145, v71
	v_mov_b32_e32 v146, v72
	v_mov_b32_e32 v147, v73
	s_cbranch_vccnz .LBB0_676
	v_lshl_or_b32 v66, v156, 4, v160
	v_readlane_b32 s0, v251, 13
	v_ashrrev_i32_e32 v67, 31, v66
	v_readlane_b32 s1, v251, 14
	v_mov_b32_dpp v144, v70 quad_perm:[2,3,0,1] row_mask:0xf bank_mask:0xf
	v_mov_b32_dpp v145, v71 quad_perm:[2,3,0,1] row_mask:0xf bank_mask:0xf
	v_lshl_add_u64 v[66:67], v[66:67], 2, s[0:1]
	s_waitcnt lgkmcnt(0)
	s_nop 1
	v_mov_b32_e32 v150, v198
	v_mov_b32_e32 v146, v202
	v_mov_b32_e32 v151, v199
	v_mov_b32_e32 v147, v203
	v_mov_b32_e32 v152, v200
	v_mov_b32_e32 v148, v204
	v_mov_b32_e32 v153, v201
	v_mov_b32_e32 v149, v205
	v_mov_b32_e32 v67, v152
	v_mov_b32_e32 v152, v151
	s_waitcnt lgkmcnt(0)
	v_pk_mul_f32 v[144:145], v[152:153], v[144:145]
	v_mov_b32_e32 v66, v150
	v_cndmask_b32_e64 v145, v145, -v145, s[46:47]
	v_cndmask_b32_e64 v144, v144, -v144, s[46:47]
	v_pk_fma_f32 v[144:145], v[70:71], v[66:67], v[144:145]
	v_mov_b32_dpp v66, v72 quad_perm:[2,3,0,1] row_mask:0xf bank_mask:0xf
	v_mov_b32_dpp v67, v73 quad_perm:[2,3,0,1] row_mask:0xf bank_mask:0xf
	v_mov_b32_e32 v151, v148
	v_mov_b32_e32 v148, v147
	v_mov_b32_e32 v150, v146
	s_waitcnt lgkmcnt(0)
	v_pk_mul_f32 v[66:67], v[148:149], v[66:67]
	s_nop 0
	v_cndmask_b32_e64 v67, v67, -v67, s[46:47]
	v_cndmask_b32_e64 v66, v66, -v66, s[46:47]
	v_pk_fma_f32 v[146:147], v[72:73], v[150:151], v[66:67]

.LBB0_678:
	s_or_b64 exec, exec, s[0:1]
	v_mov_b32_e32 v69, v68
	v_lshlrev_b32_e32 v70, 16, v142
	v_and_b32_e32 v71, 0xffff0000, v142
	v_lshlrev_b32_e32 v72, 16, v143
	v_and_b32_e32 v73, 0xffff0000, v143
	v_pk_mul_f32 v[70:71], v[68:69], v[70:71]
	v_pk_mul_f32 v[68:69], v[68:69], v[72:73]
	s_and_b64 vcc, exec, s[72:73]
	v_mov_b32_e32 v72, v70
	v_mov_b32_e32 v73, v71
	v_mov_b32_e32 v142, v68
	v_mov_b32_e32 v143, v69
	s_cbranch_vccnz .LBB0_680
	v_lshl_or_b32 v72, v156, 4, v160
	v_readlane_b32 s0, v251, 13
	v_ashrrev_i32_e32 v73, 31, v72
	v_readlane_b32 s1, v251, 14
	v_mov_b32_dpp v150, v70 quad_perm:[2,3,0,1] row_mask:0xf bank_mask:0xf
	v_mov_b32_dpp v151, v71 quad_perm:[2,3,0,1] row_mask:0xf bank_mask:0xf
	v_lshl_add_u64 v[72:73], v[72:73], 2, s[0:1]
	s_waitcnt lgkmcnt(0)
	s_nop 1
	v_mov_b32_e32 v146, v198
	v_mov_b32_e32 v142, v202
	v_mov_b32_e32 v147, v199
	v_mov_b32_e32 v143, v203
	v_mov_b32_e32 v148, v200
	v_mov_b32_e32 v144, v204
	v_mov_b32_e32 v149, v201
	v_mov_b32_e32 v145, v205
	v_mov_b32_e32 v73, v148
	v_mov_b32_e32 v148, v147
	v_mov_b32_e32 v72, v146
	s_waitcnt lgkmcnt(0)
	v_pk_mul_f32 v[146:147], v[148:149], v[150:151]
	v_mov_b32_e32 v149, v144
	v_cndmask_b32_e64 v147, v147, -v147, s[46:47]
	v_cndmask_b32_e64 v146, v146, -v146, s[46:47]
	v_pk_fma_f32 v[72:73], v[70:71], v[72:73], v[146:147]
	v_mov_b32_dpp v146, v68 quad_perm:[2,3,0,1] row_mask:0xf bank_mask:0xf
	v_mov_b32_dpp v147, v69 quad_perm:[2,3,0,1] row_mask:0xf bank_mask:0xf
	v_mov_b32_e32 v144, v143
	v_mov_b32_e32 v148, v142
	s_waitcnt lgkmcnt(0)
	v_pk_mul_f32 v[142:143], v[144:145], v[146:147]
	s_nop 0
	v_cndmask_b32_e64 v143, v143, -v143, s[46:47]
	v_cndmask_b32_e64 v142, v142, -v142, s[46:47]
	v_pk_fma_f32 v[142:143], v[68:69], v[148:149], v[142:143]
